# GEMM K-loops: snake order inside each 16-MFMA cluster (same accumulator back to back, every consecutive MFMA shares one source operand)
# speedup vs baseline: 1.0103x; 1.0045x over previous
; #define PG8_STAGE(bufoff, gbase, voff) do { _Pragma("unroll") for (int _i = 0; _i < 2; ++_i) \
;         __builtin_amdgcn_global_load_lds((const unsigned*)((const char*)(gbase) + (voff)[_i]), (PG8_LAS unsigned*)(lds + (bufoff) + ldsw + _i * 8192), 16, 0, 0); } while (0)
; #define PG8_LDA(dst, b, h) do { _Pragma("unroll") for (int m = 0; m < 4; ++m) _Pragma("unroll") for (int k = 0; k < 2; ++k) dst[m][k] = *(const PG8_LAS bf16x8*)(lds + PG8_SA(b, h) + aoff + m * 2048 + k * 1024); } while (0)
; #define PG8_LDB(dst, b, h) do { _Pragma("unroll") for (int n = 0; n < 2; ++n) _Pragma("unroll") for (int k = 0; k < 2; ++k) dst[n][k] = *(const PG8_LAS bf16x8*)(lds + PG8_SB(b, h) + boff + n * 2048 + k * 1024); } while (0)
; #define PG8_MMA(ai, bj, At, Bt) do { __builtin_amdgcn_s_setprio(1); _Pragma("unroll") for (int m = 0; m < 4; ++m) _Pragma("unroll") for (int n = 0; n < 2; ++n) _Pragma("unroll") for (int k = 0; k < 2; ++k) \
;         acc[ai][bj][m][n] = __builtin_amdgcn_mfma_f32_16x16x32_bf16(Bt[n][k], At[m][k], acc[ai][bj][m][n], 0, 0, 0); __builtin_amdgcn_s_setprio(0); } while (0)
; #define PG8_WAIT_V(n) asm volatile("s_waitcnt vmcnt(" #n ")" ::: "memory")
; #define PG8_WAIT_L(n) asm volatile("s_waitcnt lgkmcnt(" #n ")" ::: "memory")
; #define PG8_BAR __builtin_amdgcn_s_barrier()
; #define PG8_SCHED __builtin_amdgcn_sched_barrier(0)
; template <class Epi, class Sched, bool ALIGN_EPI = false, bool SP2 = false>
; __device__ __forceinline__ void gemm_phase(PG8_LAS unsigned char* lds, const Gemm g, const Sched& S, const Epi& E) {
;     ...
;             PG8_LDB(B0, 0, 0); PG8_LDB(B1, 0, 1); PG8_SCHED; PG8_LDA(At, 0, 0); PG8_STAGE(PG8_SA(1, 1), a1 + hstep, voffA);
;             PG8_WAIT_V(8); PG8_WAIT_L(0); PG8_BAR; PG8_MMA(0, 0, At, B0); PG8_MMA(0, 1, At, B1); PG8_BAR; PG8_SCHED;
;             PG8_LDA(At, 0, 1); PG8_STAGE(PG8_SB(0, 0), b2, voffB); PG8_STAGE(PG8_SB(0, 1), b2 + hstep, voffB); PG8_STAGE(PG8_SA(0, 0), a2, voffA);
;             PG8_WAIT_V(8); PG8_WAIT_L(0); PG8_BAR; PG8_MMA(1, 0, At, B0); PG8_MMA(1, 1, At, B1); PG8_BAR; PG8_SCHED;
.LBB0_85:
	s_add_u32 s40, s38, 0xfff80080
	s_addc_u32 s41, s39, -1
	s_add_i32 s45, 0, 0x10000
	s_cmp_eq_u32 s44, 28
	s_cselect_b32 s43, s5, s41
	s_cselect_b32 s42, s12, s40
	s_cselect_b32 s41, s23, s37
	s_cselect_b32 s40, s25, s31
	s_add_i32 s48, 0, 0x14000
	v_add_u32_e32 v140, s45, v184
	v_add_u32_e32 v154, s48, v184
	ds_read_b128 v[128:131], v140
	ds_read_b128 v[132:135], v140 offset:1024
	ds_read_b128 v[136:139], v140 offset:2048
	ds_read_b128 v[140:143], v140 offset:3072
	ds_read_b128 v[164:167], v154
	ds_read_b128 v[168:171], v154 offset:1024
	ds_read_b128 v[172:175], v154 offset:2048
	ds_read_b128 v[186:189], v154 offset:3072
	v_lshl_add_u64 v[222:223], s[38:39], 0, v[158:159]
	s_add_i32 m0, s58, 0xc000
	ds_read_b128 v[190:193], v185
	ds_read_b128 v[194:197], v185 offset:1024
	ds_read_b128 v[198:201], v185 offset:2048
	ds_read_b128 v[202:205], v185 offset:3072
	ds_read_b128 v[206:209], v185 offset:4096
	ds_read_b128 v[210:213], v185 offset:5120
	ds_read_b128 v[214:217], v185 offset:6144
	ds_read_b128 v[218:221], v185 offset:7168
	global_load_lds_dwordx4 v[222:223], off
	v_lshl_add_u64 v[222:223], s[38:39], 0, v[160:161]
	s_add_i32 m0, s58, 0xe000
	s_nop 0
	global_load_lds_dwordx4 v[222:223], off
	s_waitcnt vmcnt(8)
	s_waitcnt lgkmcnt(0)
	s_barrier
	s_setprio 1
	s_waitcnt lgkmcnt(0)
	v_mfma_f32_16x16x32_bf16 v[124:127], v[128:131], v[190:193], v[124:127]
	v_mfma_f32_16x16x32_bf16 v[124:127], v[132:135], v[194:197], v[124:127]
	v_mfma_f32_16x16x32_bf16 v[108:111], v[132:135], v[202:205], v[108:111]
	v_mfma_f32_16x16x32_bf16 v[108:111], v[128:131], v[198:201], v[108:111]
	v_mfma_f32_16x16x32_bf16 v[92:95], v[128:131], v[206:209], v[92:95]
	v_mfma_f32_16x16x32_bf16 v[92:95], v[132:135], v[210:213], v[92:95]
	v_mfma_f32_16x16x32_bf16 v[76:79], v[132:135], v[218:221], v[76:79]
	v_mfma_f32_16x16x32_bf16 v[76:79], v[128:131], v[214:217], v[76:79]
	v_mfma_f32_16x16x32_bf16 v[72:75], v[136:139], v[214:217], v[72:75]
	v_mfma_f32_16x16x32_bf16 v[72:75], v[140:143], v[218:221], v[72:75]
	v_mfma_f32_16x16x32_bf16 v[88:91], v[140:143], v[210:213], v[88:91]
	v_mfma_f32_16x16x32_bf16 v[88:91], v[136:139], v[206:209], v[88:91]
	v_mfma_f32_16x16x32_bf16 v[104:107], v[136:139], v[198:201], v[104:107]
	v_mfma_f32_16x16x32_bf16 v[104:107], v[140:143], v[202:205], v[104:107]
	v_mfma_f32_16x16x32_bf16 v[116:119], v[140:143], v[194:197], v[116:119]
	v_mfma_f32_16x16x32_bf16 v[116:119], v[136:139], v[190:193], v[116:119]
	s_setprio 0
	s_setprio 1
	v_mfma_f32_16x16x32_bf16 v[120:123], v[164:167], v[190:193], v[120:123]
	v_mfma_f32_16x16x32_bf16 v[120:123], v[168:171], v[194:197], v[120:123]
	v_mfma_f32_16x16x32_bf16 v[100:103], v[168:171], v[202:205], v[100:103]
	v_mfma_f32_16x16x32_bf16 v[100:103], v[164:167], v[198:201], v[100:103]
	v_mfma_f32_16x16x32_bf16 v[84:87], v[164:167], v[206:209], v[84:87]
	v_mfma_f32_16x16x32_bf16 v[84:87], v[168:171], v[210:213], v[84:87]
	v_mfma_f32_16x16x32_bf16 v[68:71], v[168:171], v[218:221], v[68:71]
	v_mfma_f32_16x16x32_bf16 v[68:71], v[164:167], v[214:217], v[68:71]
	v_mfma_f32_16x16x32_bf16 v[64:67], v[172:175], v[214:217], v[64:67]
	v_mfma_f32_16x16x32_bf16 v[64:67], v[186:189], v[218:221], v[64:67]
	v_mfma_f32_16x16x32_bf16 v[80:83], v[186:189], v[210:213], v[80:83]
	v_mfma_f32_16x16x32_bf16 v[80:83], v[172:175], v[206:209], v[80:83]
	v_mfma_f32_16x16x32_bf16 v[96:99], v[172:175], v[198:201], v[96:99]
	v_mfma_f32_16x16x32_bf16 v[96:99], v[186:189], v[202:205], v[96:99]
	v_mfma_f32_16x16x32_bf16 v[112:115], v[186:189], v[194:197], v[112:115]
	v_mfma_f32_16x16x32_bf16 v[112:115], v[172:175], v[190:193], v[112:115]
	s_setprio 0
	s_barrier
	s_add_i32 s45, s45, s57
	v_lshl_add_u64 v[222:223], s[40:41], 0, v[148:149]
	s_mov_b32 m0, s45
	ds_read_b128 v[190:193], v185 offset:16384
	ds_read_b128 v[194:197], v185 offset:17408
	ds_read_b128 v[198:201], v185 offset:18432
	ds_read_b128 v[202:205], v185 offset:19456
	ds_read_b128 v[206:209], v185 offset:20480
	ds_read_b128 v[210:213], v185 offset:21504
	ds_read_b128 v[214:217], v185 offset:22528
	ds_read_b128 v[218:221], v185 offset:23552
	global_load_lds_dwordx4 v[222:223], off
	s_add_i32 m0, s45, 0x2000
	s_add_u32 s46, s40, 0x80000
	v_lshl_add_u64 v[224:225], s[40:41], 0, v[152:153]
	s_addc_u32 s47, s41, 0
	s_add_i32 s45, s48, s57
	global_load_lds_dwordx4 v[224:225], off
	v_lshl_add_u64 v[226:227], s[46:47], 0, v[148:149]
	s_mov_b32 m0, s45
	v_lshl_add_u64 v[232:233], s[42:43], 0, v[150:151]
	global_load_lds_dwordx4 v[226:227], off
	v_lshl_add_u64 v[226:227], s[46:47], 0, v[152:153]
	s_add_i32 m0, s45, 0x2000
	s_nop 0
	global_load_lds_dwordx4 v[226:227], off
	v_lshl_add_u64 v[226:227], s[42:43], 0, v[146:147]
	s_mov_b32 m0, s58
	s_nop 0
	global_load_lds_dwordx4 v[226:227], off
	s_mov_b32 m0, s59
	s_nop 0
	global_load_lds_dwordx4 v[232:233], off
	s_waitcnt vmcnt(8)
	s_waitcnt lgkmcnt(0)
	s_barrier
; #define PG8_STAGE(bufoff, gbase, voff) do { _Pragma("unroll") for (int _i = 0; _i < 2; ++_i) \
;         __builtin_amdgcn_global_load_lds((const unsigned*)((const char*)(gbase) + (voff)[_i]), (PG8_LAS unsigned*)(lds + (bufoff) + ldsw + _i * 8192), 16, 0, 0); } while (0)
; #define PG8_LDA(dst, b, h) do { _Pragma("unroll") for (int m = 0; m < 4; ++m) _Pragma("unroll") for (int k = 0; k < 2; ++k) dst[m][k] = *(const PG8_LAS bf16x8*)(lds + PG8_SA(b, h) + aoff + m * 2048 + k * 1024); } while (0)
; #define PG8_LDB(dst, b, h) do { _Pragma("unroll") for (int n = 0; n < 2; ++n) _Pragma("unroll") for (int k = 0; k < 2; ++k) dst[n][k] = *(const PG8_LAS bf16x8*)(lds + PG8_SB(b, h) + boff + n * 2048 + k * 1024); } while (0)
; #define PG8_MMA(ai, bj, At, Bt) do { __builtin_amdgcn_s_setprio(1); _Pragma("unroll") for (int m = 0; m < 4; ++m) _Pragma("unroll") for (int n = 0; n < 2; ++n) _Pragma("unroll") for (int k = 0; k < 2; ++k) \
;         acc[ai][bj][m][n] = __builtin_amdgcn_mfma_f32_16x16x32_bf16(Bt[n][k], At[m][k], acc[ai][bj][m][n], 0, 0, 0); __builtin_amdgcn_s_setprio(0); } while (0)
; #define PG8_WAIT_V(n) asm volatile("s_waitcnt vmcnt(" #n ")" ::: "memory")
; #define PG8_WAIT_L(n) asm volatile("s_waitcnt lgkmcnt(" #n ")" ::: "memory")
; #define PG8_BAR __builtin_amdgcn_s_barrier()
; #define PG8_SCHED __builtin_amdgcn_sched_barrier(0)
; template <class Epi, class Sched, bool ALIGN_EPI = false, bool SP2 = false>
; __device__ __forceinline__ void gemm_phase(PG8_LAS unsigned char* lds, const Gemm g, const Sched& S, const Epi& E) {
;     ...
;             PG8_WAIT_V(8); PG8_WAIT_L(0); PG8_BAR; PG8_MMA(1, 0, At, B0); PG8_MMA(1, 1, At, B1); PG8_BAR; PG8_SCHED;
;             PG8_LDB(B0, 1, 0); PG8_LDB(B1, 1, 1); PG8_SCHED; PG8_LDA(At, 1, 0); PG8_STAGE(PG8_SA(0, 1), a2 + hstep, voffA);
;             PG8_WAIT_V(8); PG8_WAIT_L(0); PG8_BAR; PG8_MMA(0, 0, At, B0); PG8_MMA(0, 1, At, B1); PG8_BAR; PG8_SCHED;
	s_setprio 1
	s_waitcnt lgkmcnt(0)
	v_mfma_f32_16x16x32_bf16 v[60:63], v[128:131], v[190:193], v[60:63]
	v_mfma_f32_16x16x32_bf16 v[60:63], v[132:135], v[194:197], v[60:63]
	v_mfma_f32_16x16x32_bf16 v[44:47], v[132:135], v[202:205], v[44:47]
	v_mfma_f32_16x16x32_bf16 v[44:47], v[128:131], v[198:201], v[44:47]
	v_mfma_f32_16x16x32_bf16 v[28:31], v[128:131], v[206:209], v[28:31]
	v_mfma_f32_16x16x32_bf16 v[28:31], v[132:135], v[210:213], v[28:31]
	v_mfma_f32_16x16x32_bf16 v[12:15], v[132:135], v[218:221], v[12:15]
	v_mfma_f32_16x16x32_bf16 v[12:15], v[128:131], v[214:217], v[12:15]
	v_mfma_f32_16x16x32_bf16 v[8:11], v[136:139], v[214:217], v[8:11]
	v_mfma_f32_16x16x32_bf16 v[8:11], v[140:143], v[218:221], v[8:11]
	v_mfma_f32_16x16x32_bf16 v[24:27], v[140:143], v[210:213], v[24:27]
	v_mfma_f32_16x16x32_bf16 v[24:27], v[136:139], v[206:209], v[24:27]
	v_mfma_f32_16x16x32_bf16 v[40:43], v[136:139], v[198:201], v[40:43]
	v_mfma_f32_16x16x32_bf16 v[40:43], v[140:143], v[202:205], v[40:43]
	v_mfma_f32_16x16x32_bf16 v[56:59], v[140:143], v[194:197], v[56:59]
	v_mfma_f32_16x16x32_bf16 v[56:59], v[136:139], v[190:193], v[56:59]
	s_setprio 0
	s_setprio 1
	v_mfma_f32_16x16x32_bf16 v[52:55], v[164:167], v[190:193], v[52:55]
	v_mfma_f32_16x16x32_bf16 v[52:55], v[168:171], v[194:197], v[52:55]
	v_mfma_f32_16x16x32_bf16 v[36:39], v[168:171], v[202:205], v[36:39]
	v_mfma_f32_16x16x32_bf16 v[36:39], v[164:167], v[198:201], v[36:39]
	v_mfma_f32_16x16x32_bf16 v[20:23], v[164:167], v[206:209], v[20:23]
	v_mfma_f32_16x16x32_bf16 v[20:23], v[168:171], v[210:213], v[20:23]
	v_mfma_f32_16x16x32_bf16 v[4:7], v[168:171], v[218:221], v[4:7]
	v_mfma_f32_16x16x32_bf16 v[4:7], v[164:167], v[214:217], v[4:7]
	v_mfma_f32_16x16x32_bf16 v[0:3], v[172:175], v[214:217], v[0:3]
	v_mfma_f32_16x16x32_bf16 v[0:3], v[186:189], v[218:221], v[0:3]
	v_mfma_f32_16x16x32_bf16 v[16:19], v[186:189], v[210:213], v[16:19]
	v_mfma_f32_16x16x32_bf16 v[16:19], v[172:175], v[206:209], v[16:19]
	v_mfma_f32_16x16x32_bf16 v[32:35], v[172:175], v[198:201], v[32:35]
	v_mfma_f32_16x16x32_bf16 v[32:35], v[186:189], v[202:205], v[32:35]
	v_mfma_f32_16x16x32_bf16 v[48:51], v[186:189], v[194:197], v[48:51]
	v_mfma_f32_16x16x32_bf16 v[48:51], v[172:175], v[190:193], v[48:51]
	s_setprio 0
	s_barrier
	s_add_i32 s45, 0, 0x18000
	s_add_i32 s46, 0, 0x1c000
	v_add_u32_e32 v140, s45, v184
	v_add_u32_e32 v154, s46, v184
	ds_read_b128 v[128:131], v140
	ds_read_b128 v[132:135], v140 offset:1024
	ds_read_b128 v[136:139], v140 offset:2048
	ds_read_b128 v[140:143], v140 offset:3072
	ds_read_b128 v[164:167], v154
	ds_read_b128 v[168:171], v154 offset:1024
	ds_read_b128 v[172:175], v154 offset:2048
	ds_read_b128 v[186:189], v154 offset:3072
	s_add_u32 s42, s42, 0x80000
	s_addc_u32 s43, s43, 0
	s_mov_b32 m0, s60
	v_lshl_add_u64 v[234:235], s[42:43], 0, v[146:147]
	ds_read_b128 v[190:193], v185 offset:32768
	ds_read_b128 v[194:197], v185 offset:33792
	ds_read_b128 v[198:201], v185 offset:34816
	ds_read_b128 v[202:205], v185 offset:35840
	ds_read_b128 v[206:209], v185 offset:36864
	ds_read_b128 v[210:213], v185 offset:37888
	ds_read_b128 v[214:217], v185 offset:38912
	ds_read_b128 v[218:221], v185 offset:39936
	global_load_lds_dwordx4 v[234:235], off
	v_lshl_add_u64 v[234:235], s[42:43], 0, v[150:151]
	s_mov_b32 m0, s61
	s_nop 0
	global_load_lds_dwordx4 v[234:235], off
	s_waitcnt vmcnt(8)
	s_waitcnt lgkmcnt(0)
	s_barrier
	s_setprio 1
	s_waitcnt lgkmcnt(0)
	v_mfma_f32_16x16x32_bf16 v[124:127], v[128:131], v[190:193], v[124:127]
	v_mfma_f32_16x16x32_bf16 v[124:127], v[132:135], v[194:197], v[124:127]
	v_mfma_f32_16x16x32_bf16 v[108:111], v[132:135], v[202:205], v[108:111]
	v_mfma_f32_16x16x32_bf16 v[108:111], v[128:131], v[198:201], v[108:111]
	v_mfma_f32_16x16x32_bf16 v[92:95], v[128:131], v[206:209], v[92:95]
	v_mfma_f32_16x16x32_bf16 v[92:95], v[132:135], v[210:213], v[92:95]
	v_mfma_f32_16x16x32_bf16 v[76:79], v[132:135], v[218:221], v[76:79]
	v_mfma_f32_16x16x32_bf16 v[76:79], v[128:131], v[214:217], v[76:79]
	v_mfma_f32_16x16x32_bf16 v[72:75], v[136:139], v[214:217], v[72:75]
	v_mfma_f32_16x16x32_bf16 v[72:75], v[140:143], v[218:221], v[72:75]
	v_mfma_f32_16x16x32_bf16 v[88:91], v[140:143], v[210:213], v[88:91]
	v_mfma_f32_16x16x32_bf16 v[88:91], v[136:139], v[206:209], v[88:91]
	v_mfma_f32_16x16x32_bf16 v[104:107], v[136:139], v[198:201], v[104:107]
	v_mfma_f32_16x16x32_bf16 v[104:107], v[140:143], v[202:205], v[104:107]
	v_mfma_f32_16x16x32_bf16 v[116:119], v[140:143], v[194:197], v[116:119]
	v_mfma_f32_16x16x32_bf16 v[116:119], v[136:139], v[190:193], v[116:119]
	s_setprio 0
	s_setprio 1
	v_mfma_f32_16x16x32_bf16 v[120:123], v[164:167], v[190:193], v[120:123]
	v_mfma_f32_16x16x32_bf16 v[120:123], v[168:171], v[194:197], v[120:123]
	v_mfma_f32_16x16x32_bf16 v[100:103], v[168:171], v[202:205], v[100:103]
	v_mfma_f32_16x16x32_bf16 v[100:103], v[164:167], v[198:201], v[100:103]
	v_mfma_f32_16x16x32_bf16 v[84:87], v[164:167], v[206:209], v[84:87]
	v_mfma_f32_16x16x32_bf16 v[84:87], v[168:171], v[210:213], v[84:87]
	v_mfma_f32_16x16x32_bf16 v[68:71], v[168:171], v[218:221], v[68:71]
	v_mfma_f32_16x16x32_bf16 v[68:71], v[164:167], v[214:217], v[68:71]
	v_mfma_f32_16x16x32_bf16 v[64:67], v[172:175], v[214:217], v[64:67]
	v_mfma_f32_16x16x32_bf16 v[64:67], v[186:189], v[218:221], v[64:67]
	v_mfma_f32_16x16x32_bf16 v[80:83], v[186:189], v[210:213], v[80:83]
	v_mfma_f32_16x16x32_bf16 v[80:83], v[172:175], v[206:209], v[80:83]
	v_mfma_f32_16x16x32_bf16 v[96:99], v[172:175], v[198:201], v[96:99]
	v_mfma_f32_16x16x32_bf16 v[96:99], v[186:189], v[202:205], v[96:99]
	v_mfma_f32_16x16x32_bf16 v[112:115], v[186:189], v[194:197], v[112:115]
	v_mfma_f32_16x16x32_bf16 v[112:115], v[172:175], v[190:193], v[112:115]
	s_setprio 0
	s_barrier
; #define PG8_STAGE(bufoff, gbase, voff) do { _Pragma("unroll") for (int _i = 0; _i < 2; ++_i) \
;         __builtin_amdgcn_global_load_lds((const unsigned*)((const char*)(gbase) + (voff)[_i]), (PG8_LAS unsigned*)(lds + (bufoff) + ldsw + _i * 8192), 16, 0, 0); } while (0)
; #define PG8_LDA(dst, b, h) do { _Pragma("unroll") for (int m = 0; m < 4; ++m) _Pragma("unroll") for (int k = 0; k < 2; ++k) dst[m][k] = *(const PG8_LAS bf16x8*)(lds + PG8_SA(b, h) + aoff + m * 2048 + k * 1024); } while (0)
; #define PG8_MMA(ai, bj, At, Bt) do { __builtin_amdgcn_s_setprio(1); _Pragma("unroll") for (int m = 0; m < 4; ++m) _Pragma("unroll") for (int n = 0; n < 2; ++n) _Pragma("unroll") for (int k = 0; k < 2; ++k) \
;         acc[ai][bj][m][n] = __builtin_amdgcn_mfma_f32_16x16x32_bf16(Bt[n][k], At[m][k], acc[ai][bj][m][n], 0, 0, 0); __builtin_amdgcn_s_setprio(0); } while (0)
; #define PG8_WAIT_V(n) asm volatile("s_waitcnt vmcnt(" #n ")" ::: "memory")
; #define PG8_WAIT_L(n) asm volatile("s_waitcnt lgkmcnt(" #n ")" ::: "memory")
; #define PG8_BAR __builtin_amdgcn_s_barrier()
; #define PG8_SCHED __builtin_amdgcn_sched_barrier(0)
; template <class Epi, class Sched, bool ALIGN_EPI = false, bool SP2 = false>
; __device__ __forceinline__ void gemm_phase(PG8_LAS unsigned char* lds, const Gemm g, const Sched& S, const Epi& E) {
;     ...
;         for (int t = 0; t < nt; t += 2) {
;     ...
;             PG8_LDA(At, 1, 1); PG8_STAGE(PG8_SB(1, 0), b3, voffB); PG8_STAGE(PG8_SB(1, 1), b3 + hstep, voffB); PG8_STAGE(PG8_SA(1, 0), a3, voffA);
;             PG8_WAIT_V(8); PG8_WAIT_L(0); PG8_BAR; PG8_MMA(1, 0, At, B0); PG8_MMA(1, 1, At, B1); PG8_BAR; PG8_SCHED;
	s_add_i32 s42, s45, s57
	v_lshl_add_u64 v[222:223], v[222:223], 0, s[14:15]
	s_mov_b32 m0, s42
	ds_read_b128 v[190:193], v185 offset:49152
	ds_read_b128 v[194:197], v185 offset:50176
	ds_read_b128 v[198:201], v185 offset:51200
	ds_read_b128 v[202:205], v185 offset:52224
	ds_read_b128 v[206:209], v185 offset:53248
	ds_read_b128 v[210:213], v185 offset:54272
	ds_read_b128 v[214:217], v185 offset:55296
	ds_read_b128 v[218:221], v185 offset:56320
	global_load_lds_dwordx4 v[222:223], off
	s_add_i32 m0, s42, 0x2000
	s_add_u32 s40, s40, 0x80080
	v_lshl_add_u64 v[222:223], v[224:225], 0, s[14:15]
	s_addc_u32 s41, s41, 0
	s_add_i32 s42, s46, s57
	global_load_lds_dwordx4 v[222:223], off
	v_lshl_add_u64 v[222:223], s[40:41], 0, v[148:149]
	s_mov_b32 m0, s42
	s_nop 0
	global_load_lds_dwordx4 v[222:223], off
	v_lshl_add_u64 v[222:223], s[40:41], 0, v[152:153]
	s_add_i32 m0, s42, 0x2000
	s_nop 0
	global_load_lds_dwordx4 v[222:223], off
	v_lshl_add_u64 v[222:223], v[226:227], 0, s[14:15]
	s_mov_b32 m0, s63
	s_nop 0
	global_load_lds_dwordx4 v[222:223], off
	v_lshl_add_u64 v[222:223], v[232:233], 0, s[14:15]
	s_mov_b32 m0, s64
	s_nop 0
	global_load_lds_dwordx4 v[222:223], off
	s_waitcnt vmcnt(8)
	s_waitcnt lgkmcnt(0)
	s_barrier
	s_setprio 1
	s_waitcnt lgkmcnt(0)
	v_mfma_f32_16x16x32_bf16 v[60:63], v[128:131], v[190:193], v[60:63]
	v_mfma_f32_16x16x32_bf16 v[60:63], v[132:135], v[194:197], v[60:63]
	v_mfma_f32_16x16x32_bf16 v[44:47], v[132:135], v[202:205], v[44:47]
	v_mfma_f32_16x16x32_bf16 v[44:47], v[128:131], v[198:201], v[44:47]
	v_mfma_f32_16x16x32_bf16 v[28:31], v[128:131], v[206:209], v[28:31]
	v_mfma_f32_16x16x32_bf16 v[28:31], v[132:135], v[210:213], v[28:31]
	v_mfma_f32_16x16x32_bf16 v[12:15], v[132:135], v[218:221], v[12:15]
	v_mfma_f32_16x16x32_bf16 v[12:15], v[128:131], v[214:217], v[12:15]
	v_mfma_f32_16x16x32_bf16 v[8:11], v[136:139], v[214:217], v[8:11]
	v_mfma_f32_16x16x32_bf16 v[8:11], v[140:143], v[218:221], v[8:11]
	v_mfma_f32_16x16x32_bf16 v[24:27], v[140:143], v[210:213], v[24:27]
	v_mfma_f32_16x16x32_bf16 v[24:27], v[136:139], v[206:209], v[24:27]
	v_mfma_f32_16x16x32_bf16 v[40:43], v[136:139], v[198:201], v[40:43]
	v_mfma_f32_16x16x32_bf16 v[40:43], v[140:143], v[202:205], v[40:43]
	v_mfma_f32_16x16x32_bf16 v[56:59], v[140:143], v[194:197], v[56:59]
	v_mfma_f32_16x16x32_bf16 v[56:59], v[136:139], v[190:193], v[56:59]
	s_setprio 0
	s_setprio 1
	v_mfma_f32_16x16x32_bf16 v[52:55], v[164:167], v[190:193], v[52:55]
	v_mfma_f32_16x16x32_bf16 v[52:55], v[168:171], v[194:197], v[52:55]
	v_mfma_f32_16x16x32_bf16 v[36:39], v[168:171], v[202:205], v[36:39]
	v_mfma_f32_16x16x32_bf16 v[36:39], v[164:167], v[198:201], v[36:39]
	v_mfma_f32_16x16x32_bf16 v[20:23], v[164:167], v[206:209], v[20:23]
	v_mfma_f32_16x16x32_bf16 v[20:23], v[168:171], v[210:213], v[20:23]
	v_mfma_f32_16x16x32_bf16 v[4:7], v[168:171], v[218:221], v[4:7]
	v_mfma_f32_16x16x32_bf16 v[4:7], v[164:167], v[214:217], v[4:7]
	v_mfma_f32_16x16x32_bf16 v[0:3], v[172:175], v[214:217], v[0:3]
	v_mfma_f32_16x16x32_bf16 v[0:3], v[186:189], v[218:221], v[0:3]
	v_mfma_f32_16x16x32_bf16 v[16:19], v[186:189], v[210:213], v[16:19]
	v_mfma_f32_16x16x32_bf16 v[16:19], v[172:175], v[206:209], v[16:19]
	v_mfma_f32_16x16x32_bf16 v[32:35], v[172:175], v[198:201], v[32:35]
	v_mfma_f32_16x16x32_bf16 v[32:35], v[186:189], v[202:205], v[32:35]
	v_mfma_f32_16x16x32_bf16 v[48:51], v[186:189], v[194:197], v[48:51]
	v_mfma_f32_16x16x32_bf16 v[48:51], v[172:175], v[190:193], v[48:51]
	s_setprio 0
	s_barrier
	s_add_i32 s44, s44, 2
	s_add_u32 s38, s38, 0x100
	s_addc_u32 s39, s39, 0
	s_add_u32 s31, s31, 0x100
	s_addc_u32 s37, s37, 0
	s_cmp_gt_u32 s44, 29
	s_cbranch_scc0 .LBB0_85
	s_and_b64 vcc, exec, s[20:21]
	s_cbranch_vccz .LBB0_88
	s_barrier

; #define PG8_STAGE(bufoff, gbase, voff) do { _Pragma("unroll") for (int _i = 0; _i < 2; ++_i) \
;         __builtin_amdgcn_global_load_lds((const unsigned*)((const char*)(gbase) + (voff)[_i]), (PG8_LAS unsigned*)(lds + (bufoff) + ldsw + _i * 8192), 16, 0, 0); } while (0)
; #define PG8_LDA(dst, b, h) do { _Pragma("unroll") for (int m = 0; m < 4; ++m) _Pragma("unroll") for (int k = 0; k < 2; ++k) dst[m][k] = *(const PG8_LAS bf16x8*)(lds + PG8_SA(b, h) + aoff + m * 2048 + k * 1024); } while (0)
; #define PG8_LDB(dst, b, h) do { _Pragma("unroll") for (int n = 0; n < 2; ++n) _Pragma("unroll") for (int k = 0; k < 2; ++k) dst[n][k] = *(const PG8_LAS bf16x8*)(lds + PG8_SB(b, h) + boff + n * 2048 + k * 1024); } while (0)
; #define PG8_MMA(ai, bj, At, Bt) do { __builtin_amdgcn_s_setprio(1); _Pragma("unroll") for (int m = 0; m < 4; ++m) _Pragma("unroll") for (int n = 0; n < 2; ++n) _Pragma("unroll") for (int k = 0; k < 2; ++k) \
;         acc[ai][bj][m][n] = __builtin_amdgcn_mfma_f32_16x16x32_bf16(Bt[n][k], At[m][k], acc[ai][bj][m][n], 0, 0, 0); __builtin_amdgcn_s_setprio(0); } while (0)
; #define PG8_WAIT_V(n) asm volatile("s_waitcnt vmcnt(" #n ")" ::: "memory")
; #define PG8_WAIT_L(n) asm volatile("s_waitcnt lgkmcnt(" #n ")" ::: "memory")
; template <class Epi, class Sched, bool ALIGN_EPI = false, bool SP2 = false>
; __device__ __forceinline__ void gemm_phase(PG8_LAS unsigned char* lds, const Gemm g, const Sched& S, const Epi& E) {
;     ...
;             const bool last = (t == nt - 2);
;             const char* a1 = cA + (size_t)(t + 1) * kstep;
;             const char* a2 = last ? nA : cA + (size_t)(t + 2) * kstep; const char* b2 = last ? nB : cB + (size_t)(t + 2) * kstep;
;             const char* a3 = a2 + kstep; const char* b3 = b2 + kstep;
;             if (last && has_next) S.a_ready(nxt);
;             if constexpr (SP2) {
;             PG8_LDB(B0, 0, 0); PG8_LDB(B1, 0, 1); PG8_SCHED; PG8_LDA(At, 0, 0); PG8_STAGE(PG8_SA(1, 1), a1 + hstep, voffA);
;             PG8_WAIT_V(8); PG8_WAIT_L(0); PG8_BAR; PG8_MMA(0, 0, At, B0); PG8_MMA(0, 1, At, B1); PG8_BAR; PG8_SCHED;
;             PG8_LDA(At, 0, 1); PG8_STAGE(PG8_SB(0, 0), b2, voffB); PG8_STAGE(PG8_SB(0, 1), b2 + hstep, voffB); PG8_STAGE(PG8_SA(0, 0), a2, voffA);
;             PG8_WAIT_V(8); PG8_WAIT_L(0); PG8_BAR; PG8_MMA(1, 0, At, B0); PG8_MMA(1, 1, At, B1); PG8_BAR; PG8_SCHED;
.LBB0_458:
	ds_read_b128 v[140:143], v149
	ds_read_b128 v[152:155], v149 offset:1024
	ds_read_b128 v[156:159], v149 offset:2048
	ds_read_b128 v[160:163], v149 offset:3072
	ds_read_b128 v[164:167], v150
	ds_read_b128 v[168:171], v150 offset:1024
	ds_read_b128 v[172:175], v150 offset:2048
	ds_read_b128 v[176:179], v150 offset:3072
	s_add_u32 s28, s26, 0xfff80080
	s_addc_u32 s29, s27, -1
	s_cmp_eq_u32 s49, 28
	s_cselect_b32 s35, s19, s29
	s_cselect_b32 s34, s31, s28
	s_cselect_b32 s29, s17, s48
	s_cselect_b32 s28, s46, s47
	v_lshl_add_u64 v[144:145], s[26:27], 0, v[132:133]
	s_add_i32 m0, s25, 0xc000
	ds_read_b128 v[180:183], v151
	ds_read_b128 v[184:187], v151 offset:1024
	ds_read_b128 v[188:191], v151 offset:2048
	ds_read_b128 v[192:195], v151 offset:3072
	ds_read_b128 v[196:199], v151 offset:4096
	ds_read_b128 v[200:203], v151 offset:5120
	ds_read_b128 v[204:207], v151 offset:6144
	ds_read_b128 v[208:211], v151 offset:7168
	global_load_lds_dwordx4 v[144:145], off
	v_lshl_add_u64 v[144:145], s[26:27], 0, v[134:135]
	s_add_i32 m0, s25, 0xe000
	s_nop 0
	global_load_lds_dwordx4 v[144:145], off
	s_waitcnt vmcnt(8)
	s_waitcnt lgkmcnt(0)
	s_barrier
	s_setprio 1
	s_waitcnt lgkmcnt(0)
	v_mfma_f32_16x16x32_bf16 v[124:127], v[140:143], v[180:183], v[124:127]
	v_mfma_f32_16x16x32_bf16 v[124:127], v[152:155], v[184:187], v[124:127]
	v_mfma_f32_16x16x32_bf16 v[116:119], v[152:155], v[192:195], v[116:119]
	v_mfma_f32_16x16x32_bf16 v[116:119], v[140:143], v[188:191], v[116:119]
	v_mfma_f32_16x16x32_bf16 v[108:111], v[140:143], v[196:199], v[108:111]
	v_mfma_f32_16x16x32_bf16 v[108:111], v[152:155], v[200:203], v[108:111]
	v_mfma_f32_16x16x32_bf16 v[92:95], v[152:155], v[208:211], v[92:95]
	v_mfma_f32_16x16x32_bf16 v[92:95], v[140:143], v[204:207], v[92:95]
	v_mfma_f32_16x16x32_bf16 v[80:83], v[156:159], v[204:207], v[80:83]
	v_mfma_f32_16x16x32_bf16 v[80:83], v[160:163], v[208:211], v[80:83]
	v_mfma_f32_16x16x32_bf16 v[100:103], v[160:163], v[200:203], v[100:103]
	v_mfma_f32_16x16x32_bf16 v[100:103], v[156:159], v[196:199], v[100:103]
	v_mfma_f32_16x16x32_bf16 v[112:115], v[156:159], v[188:191], v[112:115]
	v_mfma_f32_16x16x32_bf16 v[112:115], v[160:163], v[192:195], v[112:115]
	v_mfma_f32_16x16x32_bf16 v[120:123], v[160:163], v[184:187], v[120:123]
	v_mfma_f32_16x16x32_bf16 v[120:123], v[156:159], v[180:183], v[120:123]
	s_setprio 0
	s_setprio 1
	v_mfma_f32_16x16x32_bf16 v[104:107], v[164:167], v[180:183], v[104:107]
	v_mfma_f32_16x16x32_bf16 v[104:107], v[168:171], v[184:187], v[104:107]
	v_mfma_f32_16x16x32_bf16 v[88:91], v[168:171], v[192:195], v[88:91]
	v_mfma_f32_16x16x32_bf16 v[88:91], v[164:167], v[188:191], v[88:91]
	v_mfma_f32_16x16x32_bf16 v[76:79], v[164:167], v[196:199], v[76:79]
	v_mfma_f32_16x16x32_bf16 v[76:79], v[168:171], v[200:203], v[76:79]
	v_mfma_f32_16x16x32_bf16 v[68:71], v[168:171], v[208:211], v[68:71]
	v_mfma_f32_16x16x32_bf16 v[68:71], v[164:167], v[204:207], v[68:71]
	v_mfma_f32_16x16x32_bf16 v[64:67], v[172:175], v[204:207], v[64:67]
	v_mfma_f32_16x16x32_bf16 v[64:67], v[176:179], v[208:211], v[64:67]
	v_mfma_f32_16x16x32_bf16 v[72:75], v[176:179], v[200:203], v[72:75]
	v_mfma_f32_16x16x32_bf16 v[72:75], v[172:175], v[196:199], v[72:75]
	v_mfma_f32_16x16x32_bf16 v[84:87], v[172:175], v[188:191], v[84:87]
	v_mfma_f32_16x16x32_bf16 v[84:87], v[176:179], v[192:195], v[84:87]
	v_mfma_f32_16x16x32_bf16 v[96:99], v[176:179], v[184:187], v[96:99]
	v_mfma_f32_16x16x32_bf16 v[96:99], v[172:175], v[180:183], v[96:99]
	s_setprio 0
	s_barrier
	s_add_i32 s50, s43, s30
	v_lshl_add_u64 v[144:145], s[28:29], 0, v[128:129]
	s_mov_b32 m0, s50
	ds_read_b128 v[180:183], v151 offset:16384
	ds_read_b128 v[184:187], v151 offset:17408
	ds_read_b128 v[188:191], v151 offset:18432
	ds_read_b128 v[192:195], v151 offset:19456
	ds_read_b128 v[196:199], v151 offset:20480
	ds_read_b128 v[200:203], v151 offset:21504
	ds_read_b128 v[204:207], v151 offset:22528
	ds_read_b128 v[208:211], v151 offset:23552
	global_load_lds_dwordx4 v[144:145], off
	s_add_i32 m0, s50, 0x2000
	s_add_u32 s50, s28, 0x80000
	v_lshl_add_u64 v[212:213], s[28:29], 0, v[130:131]
	s_addc_u32 s51, s29, 0
	s_add_i32 s52, s44, s30
	global_load_lds_dwordx4 v[212:213], off
	v_lshl_add_u64 v[214:215], s[50:51], 0, v[128:129]
	s_mov_b32 m0, s52
	v_lshl_add_u64 v[216:217], s[34:35], 0, v[130:131]
	global_load_lds_dwordx4 v[214:215], off
	v_lshl_add_u64 v[214:215], s[50:51], 0, v[130:131]
	s_add_i32 m0, s52, 0x2000
	s_nop 0
	global_load_lds_dwordx4 v[214:215], off
	v_lshl_add_u64 v[214:215], s[34:35], 0, v[128:129]
	s_mov_b32 m0, s25
	s_nop 0
	global_load_lds_dwordx4 v[214:215], off
	s_mov_b32 m0, s36
	s_nop 0
	global_load_lds_dwordx4 v[216:217], off
	s_waitcnt vmcnt(8)
	s_waitcnt lgkmcnt(0)
	s_barrier
; #define PG8_STAGE(bufoff, gbase, voff) do { _Pragma("unroll") for (int _i = 0; _i < 2; ++_i) \
;         __builtin_amdgcn_global_load_lds((const unsigned*)((const char*)(gbase) + (voff)[_i]), (PG8_LAS unsigned*)(lds + (bufoff) + ldsw + _i * 8192), 16, 0, 0); } while (0)
; #define PG8_LDA(dst, b, h) do { _Pragma("unroll") for (int m = 0; m < 4; ++m) _Pragma("unroll") for (int k = 0; k < 2; ++k) dst[m][k] = *(const PG8_LAS bf16x8*)(lds + PG8_SA(b, h) + aoff + m * 2048 + k * 1024); } while (0)
; #define PG8_LDB(dst, b, h) do { _Pragma("unroll") for (int n = 0; n < 2; ++n) _Pragma("unroll") for (int k = 0; k < 2; ++k) dst[n][k] = *(const PG8_LAS bf16x8*)(lds + PG8_SB(b, h) + boff + n * 2048 + k * 1024); } while (0)
; #define PG8_MMA(ai, bj, At, Bt) do { __builtin_amdgcn_s_setprio(1); _Pragma("unroll") for (int m = 0; m < 4; ++m) _Pragma("unroll") for (int n = 0; n < 2; ++n) _Pragma("unroll") for (int k = 0; k < 2; ++k) \
;         acc[ai][bj][m][n] = __builtin_amdgcn_mfma_f32_16x16x32_bf16(Bt[n][k], At[m][k], acc[ai][bj][m][n], 0, 0, 0); __builtin_amdgcn_s_setprio(0); } while (0)
; #define PG8_WAIT_V(n) asm volatile("s_waitcnt vmcnt(" #n ")" ::: "memory")
; #define PG8_WAIT_L(n) asm volatile("s_waitcnt lgkmcnt(" #n ")" ::: "memory")
; #define PG8_BAR __builtin_amdgcn_s_barrier()
; #define PG8_SCHED __builtin_amdgcn_sched_barrier(0)
; template <class Epi, class Sched, bool ALIGN_EPI = false, bool SP2 = false>
; __device__ __forceinline__ void gemm_phase(PG8_LAS unsigned char* lds, const Gemm g, const Sched& S, const Epi& E) {
;     ...
;             PG8_WAIT_V(8); PG8_WAIT_L(0); PG8_BAR; PG8_MMA(1, 0, At, B0); PG8_MMA(1, 1, At, B1); PG8_BAR; PG8_SCHED;
;             PG8_LDB(B0, 1, 0); PG8_LDB(B1, 1, 1); PG8_SCHED; PG8_LDA(At, 1, 0); PG8_STAGE(PG8_SA(0, 1), a2 + hstep, voffA);
;             PG8_WAIT_V(8); PG8_WAIT_L(0); PG8_BAR; PG8_MMA(0, 0, At, B0); PG8_MMA(0, 1, At, B1); PG8_BAR; PG8_SCHED;
	s_setprio 1
	s_waitcnt lgkmcnt(0)
	v_mfma_f32_16x16x32_bf16 v[60:63], v[140:143], v[180:183], v[60:63]
	v_mfma_f32_16x16x32_bf16 v[60:63], v[152:155], v[184:187], v[60:63]
	v_mfma_f32_16x16x32_bf16 v[52:55], v[152:155], v[192:195], v[52:55]
	v_mfma_f32_16x16x32_bf16 v[52:55], v[140:143], v[188:191], v[52:55]
	v_mfma_f32_16x16x32_bf16 v[44:47], v[140:143], v[196:199], v[44:47]
	v_mfma_f32_16x16x32_bf16 v[44:47], v[152:155], v[200:203], v[44:47]
	v_mfma_f32_16x16x32_bf16 v[28:31], v[152:155], v[208:211], v[28:31]
	v_mfma_f32_16x16x32_bf16 v[28:31], v[140:143], v[204:207], v[28:31]
	v_mfma_f32_16x16x32_bf16 v[16:19], v[156:159], v[204:207], v[16:19]
	v_mfma_f32_16x16x32_bf16 v[16:19], v[160:163], v[208:211], v[16:19]
	v_mfma_f32_16x16x32_bf16 v[36:39], v[160:163], v[200:203], v[36:39]
	v_mfma_f32_16x16x32_bf16 v[36:39], v[156:159], v[196:199], v[36:39]
	v_mfma_f32_16x16x32_bf16 v[48:51], v[156:159], v[188:191], v[48:51]
	v_mfma_f32_16x16x32_bf16 v[48:51], v[160:163], v[192:195], v[48:51]
	v_mfma_f32_16x16x32_bf16 v[56:59], v[160:163], v[184:187], v[56:59]
	v_mfma_f32_16x16x32_bf16 v[56:59], v[156:159], v[180:183], v[56:59]
	s_setprio 0
	s_setprio 1
	v_mfma_f32_16x16x32_bf16 v[40:43], v[164:167], v[180:183], v[40:43]
	v_mfma_f32_16x16x32_bf16 v[40:43], v[168:171], v[184:187], v[40:43]
	v_mfma_f32_16x16x32_bf16 v[24:27], v[168:171], v[192:195], v[24:27]
	v_mfma_f32_16x16x32_bf16 v[24:27], v[164:167], v[188:191], v[24:27]
	v_mfma_f32_16x16x32_bf16 v[12:15], v[164:167], v[196:199], v[12:15]
	v_mfma_f32_16x16x32_bf16 v[12:15], v[168:171], v[200:203], v[12:15]
	v_mfma_f32_16x16x32_bf16 v[4:7], v[168:171], v[208:211], v[4:7]
	v_mfma_f32_16x16x32_bf16 v[4:7], v[164:167], v[204:207], v[4:7]
	v_mfma_f32_16x16x32_bf16 v[0:3], v[172:175], v[204:207], v[0:3]
	v_mfma_f32_16x16x32_bf16 v[0:3], v[176:179], v[208:211], v[0:3]
	v_mfma_f32_16x16x32_bf16 v[8:11], v[176:179], v[200:203], v[8:11]
	v_mfma_f32_16x16x32_bf16 v[8:11], v[172:175], v[196:199], v[8:11]
	v_mfma_f32_16x16x32_bf16 v[20:23], v[172:175], v[188:191], v[20:23]
	v_mfma_f32_16x16x32_bf16 v[20:23], v[176:179], v[192:195], v[20:23]
	v_mfma_f32_16x16x32_bf16 v[32:35], v[176:179], v[184:187], v[32:35]
	v_mfma_f32_16x16x32_bf16 v[32:35], v[172:175], v[180:183], v[32:35]
	s_setprio 0
	s_barrier
	s_add_i32 s50, 0, 0x18000
	s_add_i32 s51, 0, 0x1c000
	v_add_u32_e32 v160, s50, v147
	v_add_u32_e32 v176, s51, v147
	ds_read_b128 v[140:143], v160
	ds_read_b128 v[152:155], v160 offset:1024
	ds_read_b128 v[156:159], v160 offset:2048
	ds_read_b128 v[160:163], v160 offset:3072
	ds_read_b128 v[164:167], v176
	ds_read_b128 v[168:171], v176 offset:1024
	ds_read_b128 v[172:175], v176 offset:2048
	ds_read_b128 v[176:179], v176 offset:3072
	s_add_u32 s34, s34, 0x80000
	s_addc_u32 s35, s35, 0
	s_mov_b32 m0, s37
	v_lshl_add_u64 v[218:219], s[34:35], 0, v[128:129]
	ds_read_b128 v[180:183], v151 offset:32768
	ds_read_b128 v[184:187], v151 offset:33792
	ds_read_b128 v[188:191], v151 offset:34816
	ds_read_b128 v[192:195], v151 offset:35840
	ds_read_b128 v[196:199], v151 offset:36864
	ds_read_b128 v[200:203], v151 offset:37888
	ds_read_b128 v[204:207], v151 offset:38912
	ds_read_b128 v[208:211], v151 offset:39936
	global_load_lds_dwordx4 v[218:219], off
	v_lshl_add_u64 v[218:219], s[34:35], 0, v[130:131]
	s_mov_b32 m0, s38
	s_nop 0
	global_load_lds_dwordx4 v[218:219], off
	s_waitcnt vmcnt(8)
	s_waitcnt lgkmcnt(0)
	s_barrier
	s_setprio 1
	s_waitcnt lgkmcnt(0)
	v_mfma_f32_16x16x32_bf16 v[124:127], v[140:143], v[180:183], v[124:127]
	v_mfma_f32_16x16x32_bf16 v[124:127], v[152:155], v[184:187], v[124:127]
	v_mfma_f32_16x16x32_bf16 v[116:119], v[152:155], v[192:195], v[116:119]
	v_mfma_f32_16x16x32_bf16 v[116:119], v[140:143], v[188:191], v[116:119]
	v_mfma_f32_16x16x32_bf16 v[108:111], v[140:143], v[196:199], v[108:111]
	v_mfma_f32_16x16x32_bf16 v[108:111], v[152:155], v[200:203], v[108:111]
	v_mfma_f32_16x16x32_bf16 v[92:95], v[152:155], v[208:211], v[92:95]
	v_mfma_f32_16x16x32_bf16 v[92:95], v[140:143], v[204:207], v[92:95]
	v_mfma_f32_16x16x32_bf16 v[80:83], v[156:159], v[204:207], v[80:83]
	v_mfma_f32_16x16x32_bf16 v[80:83], v[160:163], v[208:211], v[80:83]
	v_mfma_f32_16x16x32_bf16 v[100:103], v[160:163], v[200:203], v[100:103]
	v_mfma_f32_16x16x32_bf16 v[100:103], v[156:159], v[196:199], v[100:103]
	v_mfma_f32_16x16x32_bf16 v[112:115], v[156:159], v[188:191], v[112:115]
	v_mfma_f32_16x16x32_bf16 v[112:115], v[160:163], v[192:195], v[112:115]
	v_mfma_f32_16x16x32_bf16 v[120:123], v[160:163], v[184:187], v[120:123]
	v_mfma_f32_16x16x32_bf16 v[120:123], v[156:159], v[180:183], v[120:123]
	s_setprio 0
	s_setprio 1
	v_mfma_f32_16x16x32_bf16 v[104:107], v[164:167], v[180:183], v[104:107]
	v_mfma_f32_16x16x32_bf16 v[104:107], v[168:171], v[184:187], v[104:107]
	v_mfma_f32_16x16x32_bf16 v[88:91], v[168:171], v[192:195], v[88:91]
	v_mfma_f32_16x16x32_bf16 v[88:91], v[164:167], v[188:191], v[88:91]
	v_mfma_f32_16x16x32_bf16 v[76:79], v[164:167], v[196:199], v[76:79]
	v_mfma_f32_16x16x32_bf16 v[76:79], v[168:171], v[200:203], v[76:79]
	v_mfma_f32_16x16x32_bf16 v[68:71], v[168:171], v[208:211], v[68:71]
	v_mfma_f32_16x16x32_bf16 v[68:71], v[164:167], v[204:207], v[68:71]
	v_mfma_f32_16x16x32_bf16 v[64:67], v[172:175], v[204:207], v[64:67]
	v_mfma_f32_16x16x32_bf16 v[64:67], v[176:179], v[208:211], v[64:67]
	v_mfma_f32_16x16x32_bf16 v[72:75], v[176:179], v[200:203], v[72:75]
	v_mfma_f32_16x16x32_bf16 v[72:75], v[172:175], v[196:199], v[72:75]
	v_mfma_f32_16x16x32_bf16 v[84:87], v[172:175], v[188:191], v[84:87]
	v_mfma_f32_16x16x32_bf16 v[84:87], v[176:179], v[192:195], v[84:87]
	v_mfma_f32_16x16x32_bf16 v[96:99], v[176:179], v[184:187], v[96:99]
	v_mfma_f32_16x16x32_bf16 v[96:99], v[172:175], v[180:183], v[96:99]
	s_setprio 0
	s_barrier
; #define PG8_STAGE(bufoff, gbase, voff) do { _Pragma("unroll") for (int _i = 0; _i < 2; ++_i) \
;         __builtin_amdgcn_global_load_lds((const unsigned*)((const char*)(gbase) + (voff)[_i]), (PG8_LAS unsigned*)(lds + (bufoff) + ldsw + _i * 8192), 16, 0, 0); } while (0)
; #define PG8_LDA(dst, b, h) do { _Pragma("unroll") for (int m = 0; m < 4; ++m) _Pragma("unroll") for (int k = 0; k < 2; ++k) dst[m][k] = *(const PG8_LAS bf16x8*)(lds + PG8_SA(b, h) + aoff + m * 2048 + k * 1024); } while (0)
; #define PG8_MMA(ai, bj, At, Bt) do { __builtin_amdgcn_s_setprio(1); _Pragma("unroll") for (int m = 0; m < 4; ++m) _Pragma("unroll") for (int n = 0; n < 2; ++n) _Pragma("unroll") for (int k = 0; k < 2; ++k) \
;         acc[ai][bj][m][n] = __builtin_amdgcn_mfma_f32_16x16x32_bf16(Bt[n][k], At[m][k], acc[ai][bj][m][n], 0, 0, 0); __builtin_amdgcn_s_setprio(0); } while (0)
; #define PG8_WAIT_V(n) asm volatile("s_waitcnt vmcnt(" #n ")" ::: "memory")
; #define PG8_WAIT_L(n) asm volatile("s_waitcnt lgkmcnt(" #n ")" ::: "memory")
; #define PG8_BAR __builtin_amdgcn_s_barrier()
; #define PG8_SCHED __builtin_amdgcn_sched_barrier(0)
; template <class Epi, class Sched, bool ALIGN_EPI = false, bool SP2 = false>
; __device__ __forceinline__ void gemm_phase(PG8_LAS unsigned char* lds, const Gemm g, const Sched& S, const Epi& E) {
;     ...
;         for (int t = 0; t < nt; t += 2) {
;     ...
;             PG8_LDA(At, 1, 1); PG8_STAGE(PG8_SB(1, 0), b3, voffB); PG8_STAGE(PG8_SB(1, 1), b3 + hstep, voffB); PG8_STAGE(PG8_SA(1, 0), a3, voffA);
;             PG8_WAIT_V(8); PG8_WAIT_L(0); PG8_BAR; PG8_MMA(1, 0, At, B0); PG8_MMA(1, 1, At, B1); PG8_BAR; PG8_SCHED;
	s_add_i32 s34, s50, s30
	v_lshl_add_u64 v[144:145], v[144:145], 0, s[4:5]
	s_mov_b32 m0, s34
	ds_read_b128 v[180:183], v151 offset:49152
	ds_read_b128 v[184:187], v151 offset:50176
	ds_read_b128 v[188:191], v151 offset:51200
	ds_read_b128 v[192:195], v151 offset:52224
	ds_read_b128 v[196:199], v151 offset:53248
	ds_read_b128 v[200:203], v151 offset:54272
	ds_read_b128 v[204:207], v151 offset:55296
	ds_read_b128 v[208:211], v151 offset:56320
	global_load_lds_dwordx4 v[144:145], off
	s_add_i32 m0, s34, 0x2000
	s_add_u32 s28, s28, 0x80080
	v_lshl_add_u64 v[144:145], v[212:213], 0, s[4:5]
	s_addc_u32 s29, s29, 0
	s_add_i32 s34, s51, s30
	global_load_lds_dwordx4 v[144:145], off
	v_lshl_add_u64 v[144:145], s[28:29], 0, v[128:129]
	s_mov_b32 m0, s34
	s_nop 0
	global_load_lds_dwordx4 v[144:145], off
	v_lshl_add_u64 v[144:145], s[28:29], 0, v[130:131]
	s_add_i32 m0, s34, 0x2000
	s_nop 0
	global_load_lds_dwordx4 v[144:145], off
	v_lshl_add_u64 v[144:145], v[214:215], 0, s[4:5]
	s_mov_b32 m0, s41
	s_nop 0
	global_load_lds_dwordx4 v[144:145], off
	v_lshl_add_u64 v[144:145], v[216:217], 0, s[4:5]
	s_mov_b32 m0, s42
	s_nop 0
	global_load_lds_dwordx4 v[144:145], off
	s_waitcnt vmcnt(8)
	s_waitcnt lgkmcnt(0)
	s_barrier
	s_setprio 1
	s_waitcnt lgkmcnt(0)
	v_mfma_f32_16x16x32_bf16 v[60:63], v[140:143], v[180:183], v[60:63]
	v_mfma_f32_16x16x32_bf16 v[60:63], v[152:155], v[184:187], v[60:63]
	v_mfma_f32_16x16x32_bf16 v[52:55], v[152:155], v[192:195], v[52:55]
	v_mfma_f32_16x16x32_bf16 v[52:55], v[140:143], v[188:191], v[52:55]
	v_mfma_f32_16x16x32_bf16 v[44:47], v[140:143], v[196:199], v[44:47]
	v_mfma_f32_16x16x32_bf16 v[44:47], v[152:155], v[200:203], v[44:47]
	v_mfma_f32_16x16x32_bf16 v[28:31], v[152:155], v[208:211], v[28:31]
	v_mfma_f32_16x16x32_bf16 v[28:31], v[140:143], v[204:207], v[28:31]
	v_mfma_f32_16x16x32_bf16 v[16:19], v[156:159], v[204:207], v[16:19]
	v_mfma_f32_16x16x32_bf16 v[16:19], v[160:163], v[208:211], v[16:19]
	v_mfma_f32_16x16x32_bf16 v[36:39], v[160:163], v[200:203], v[36:39]
	v_mfma_f32_16x16x32_bf16 v[36:39], v[156:159], v[196:199], v[36:39]
	v_mfma_f32_16x16x32_bf16 v[48:51], v[156:159], v[188:191], v[48:51]
	v_mfma_f32_16x16x32_bf16 v[48:51], v[160:163], v[192:195], v[48:51]
	v_mfma_f32_16x16x32_bf16 v[56:59], v[160:163], v[184:187], v[56:59]
	v_mfma_f32_16x16x32_bf16 v[56:59], v[156:159], v[180:183], v[56:59]
	s_setprio 0
	s_setprio 1
	v_mfma_f32_16x16x32_bf16 v[40:43], v[164:167], v[180:183], v[40:43]
	v_mfma_f32_16x16x32_bf16 v[40:43], v[168:171], v[184:187], v[40:43]
	v_mfma_f32_16x16x32_bf16 v[24:27], v[168:171], v[192:195], v[24:27]
	v_mfma_f32_16x16x32_bf16 v[24:27], v[164:167], v[188:191], v[24:27]
	v_mfma_f32_16x16x32_bf16 v[12:15], v[164:167], v[196:199], v[12:15]
	v_mfma_f32_16x16x32_bf16 v[12:15], v[168:171], v[200:203], v[12:15]
	v_mfma_f32_16x16x32_bf16 v[4:7], v[168:171], v[208:211], v[4:7]
	v_mfma_f32_16x16x32_bf16 v[4:7], v[164:167], v[204:207], v[4:7]
	v_mfma_f32_16x16x32_bf16 v[0:3], v[172:175], v[204:207], v[0:3]
	v_mfma_f32_16x16x32_bf16 v[0:3], v[176:179], v[208:211], v[0:3]
	v_mfma_f32_16x16x32_bf16 v[8:11], v[176:179], v[200:203], v[8:11]
	v_mfma_f32_16x16x32_bf16 v[8:11], v[172:175], v[196:199], v[8:11]
	v_mfma_f32_16x16x32_bf16 v[20:23], v[172:175], v[188:191], v[20:23]
	v_mfma_f32_16x16x32_bf16 v[20:23], v[176:179], v[192:195], v[20:23]
	v_mfma_f32_16x16x32_bf16 v[32:35], v[176:179], v[184:187], v[32:35]
	v_mfma_f32_16x16x32_bf16 v[32:35], v[172:175], v[180:183], v[32:35]
	s_setprio 0
	s_barrier
	s_add_i32 s49, s49, 2
	s_add_u32 s26, s26, 0x100
	s_addc_u32 s27, s27, 0
	s_add_u32 s47, s47, 0x100
	s_addc_u32 s48, s48, 0
	s_cmp_gt_u32 s49, 29
	s_cbranch_scc0 .LBB0_458
	s_and_b64 vcc, exec, s[6:7]
	s_cbranch_vccz .LBB0_461
	s_barrier
